# memory-V transposes moved to wave 2 of the first 64 workgroups so they overlap the V transposes on waves 0-1
# speedup vs baseline: 1.0016x; 1.0016x over previous
; __global__ void __launch_bounds__(512, 2) fwd_megakernel(Args args) {
;     ...
;             for (int it = gw; it < 64; it += NGW) {
;                 const int bh = it >> 2, tt = it & 3, b = bh >> 2, hh = bh & 3;
;                 transpose64x128(MKV + ((size_t)b * 256 + 64 * tt) * 1024 + 512 + hh * 128, 1024, MVT + (size_t)bh * 128 * 256 + 64 * tt, 256, lane);
.LBB0_557:
	s_add_i32 s8, s9, 6
	s_and_b32 s8, s8, 7
	s_mul_i32 s8, s8, s66
	s_add_i32 s8, s8, s86
	s_cmp_gt_i32 s8, 63
	s_movk_i32 s10, 0x6000
	s_mov_b32 s11, 0x8000
	s_mov_b32 s16, 0xa000
	s_mov_b32 s17, 0xc000
	s_mov_b32 s18, 0xe000
	s_cbranch_scc1 .LBB0_560
	s_add_u32 s0, s44, 0x23d00000
	s_addc_u32 s1, s45, 0
	v_lshlrev_b32_e32 v0, 10, v64
	s_lshl_b32 s2, s8, 6
	s_nop 0
	v_lshlrev_b32_e32 v160, 1, v0
	v_lshlrev_b32_e32 v28, 1, v64
